# static s_setprio 1 for waves 4-7 (stream 1) during differential-attention items, on top of x loads nt
# speedup vs baseline: 1.0290x; 1.0290x over previous
.LBB0_244:
	s_setprio 0
	s_mov_b64 s[4:5], 0

.LBB0_250:
	s_or_b64 exec, exec, s[4:5]
	v_mov_b32_e32 v0, s63
	s_waitcnt lgkmcnt(0)
	s_barrier
	ds_read_b32 v0, v0
	s_mov_b64 s[4:5], -1
	s_waitcnt lgkmcnt(0)
	s_barrier
	v_readfirstlane_b32 s68, v0
	s_cmpk_gt_i32 s68, 0x2ff
	s_cbranch_scc1 .LBB0_245
	s_cmpk_gt_i32 s68, 0xff
	s_cbranch_scc0 .LBB0_296
	s_add_i32 s20, s68, 0xffffff00
	s_cmpk_gt_u32 s68, 0x1ff
	s_cbranch_scc0 .LBB0_268
	v_mov_b32_e32 v32, v254
	s_and_b32 s8, s68, 63
	v_readfirstlane_b32 s36, v32
	s_ashr_i32 s6, s36, 6
	s_and_b32 s69, s6, 3
	s_lshr_b32 s76, s20, 7
	s_lshl_b32 s5, s8, 7
	s_lshl_b32 s4, s69, 5
	s_ashr_i32 s37, s36, 8
	s_cmp_lg_u32 s37, 1
	s_cbranch_scc1 .Lsp_skip1
	s_setprio 1
.Lsp_skip1:
	s_sub_i32 s26, 3, s76
	s_bfe_u32 s7, s68, 0x10006
	s_or_b32 s4, s4, s5
	s_cmp_eq_u32 s76, 3
	v_mov_b32_e32 v0, s60
	v_mov_b32_e32 v1, s59
	s_cselect_b64 vcc, -1, 0
	v_cndmask_b32_e32 v0, v0, v1, vcc
	v_cvt_i32_f32_e32 v0, v0
	v_and_or_b32 v159, v32, 31, s4
	v_bfe_u32 v34, v32, 4, 2
	v_bfe_u32 v33, v32, 5, 1
	v_readfirstlane_b32 s4, v0
	s_sub_i32 s9, s5, s4
	s_sub_i32 s22, s9, 63
	s_ashr_i32 s9, s9, 6
	s_cmp_gt_i32 s22, 0
	s_cselect_b32 s72, s9, 0
	s_add_i32 s4, s4, s5
	s_addk_i32 s4, 0x7f
	s_ashr_i32 s9, s4, 6
	s_lshl_b32 s71, s8, 1
	s_or_b32 s4, s71, 1
	s_min_i32 s9, s9, 0x7f
	s_sub_i32 s22, s71, s72
	s_sub_i32 s9, s9, s4
	s_add_i32 s70, s22, s9
	s_lshl_b32 s9, s7, 3
	s_lshl_b32 s22, s26, 1
	s_or_b32 s9, s22, s9
	s_lshl_b32 s22, s9, 20
	s_add_u32 s22, s45, s22
	s_addc_u32 s23, s46, 0
	v_bfe_u32 v0, v32, 3, 3
	s_add_u32 s24, s22, 0x100000
	v_lshl_or_b32 v2, s6, 3, v0
	s_addc_u32 s25, s23, 0
	s_lshl_b32 s27, s7, 23
	s_lshl_b32 s7, s26, 21
	s_lshl_b32 s29, s6, 10
	s_add_i32 s6, s37, s9
	s_or_b32 s28, s7, s27
	s_ashr_i32 s7, s6, 31
	v_lshrrev_b32_e32 v0, 1, v2
	s_lshl_b64 s[6:7], s[6:7], 20
	v_xor_b32_e32 v0, v0, v32
	s_add_u32 s6, s38, s6
	v_lshlrev_b32_e32 v3, 4, v0
	v_and_b32_e32 v36, 15, v32
	v_lshlrev_b32_e32 v0, 2, v34
	s_addc_u32 s7, s44, s7
	v_lshlrev_b32_e32 v130, 7, v159
	v_bitop3_b32 v5, v0, v36, s69 bitop3:0x36
	v_lshl_add_u64 v[0:1], s[6:7], 0, v[130:131]
	v_lshlrev_b32_e32 v156, 4, v33
	v_mov_b32_e32 v157, v131
	v_lshl_add_u64 v[0:1], v[0:1], 0, v[156:157]
	s_waitcnt vmcnt(0)
	global_load_dwordx4 v[144:147], v[0:1], off
	global_load_dwordx4 v[140:143], v[0:1], off offset:32
	global_load_dwordx4 v[136:139], v[0:1], off offset:64
	global_load_dwordx4 v[132:135], v[0:1], off offset:96
	v_lshlrev_b32_e32 v1, 1, v32
	v_lshrrev_b32_e32 v37, 1, v32
	v_and_b32_e32 v0, 19, v32
	v_and_b32_e32 v1, 8, v1
	v_and_b32_e32 v6, 4, v37
	v_or3_b32 v35, v6, v0, v1
	v_lshlrev_b32_e32 v0, 7, v2
	s_add_u32 s6, s47, s28
	s_addc_u32 s7, s48, 0
	s_lshl_b32 s9, s37, 13
	v_and_or_b32 v185, v3, s64, v0
	v_lshl_or_b32 v4, v34, 8, s29
	v_lshl_or_b32 v0, v35, 7, s9
	v_lshl_add_u32 v1, s8, 14, v185
	s_add_i32 s75, s29, 0
	s_mov_b32 s9, m0
	s_mov_b32 m0, s75
	s_nop 0
	global_load_lds_dwordx4 v1, s[22:23]
	s_mov_b32 m0, s9
	v_lshl_or_b32 v170, v5, 4, v4
	s_add_i32 s77, s75, 0x2000
	s_mov_b32 s9, m0
	s_mov_b32 m0, s77
	s_nop 0
	global_load_lds_dwordx4 v1, s[24:25]
	s_mov_b32 m0, s9
	s_lshl_b32 s8, s8, 15
	v_lshrrev_b32_e32 v8, 1, v35
	v_add_u32_e32 v169, 0x2000, v170
	v_add_u32_e32 v1, s8, v170
	s_add_i32 s73, s75, 0x4000
	s_mov_b32 s9, m0
	s_mov_b32 m0, s73
	s_nop 0
	global_load_lds_dwordx4 v1, s[6:7]
	s_mov_b32 m0, s9
	v_add_u32_e32 v1, s8, v169
	s_add_i32 s74, s75, 0x6000
	s_mov_b32 s8, m0
	s_mov_b32 m0, s74
	s_nop 0
	global_load_lds_dwordx4 v1, s[6:7]
	s_mov_b32 m0, s8
	v_add_u32_e32 v9, 0, v0
	v_bitop3_b32 v0, v8, v33, 7 bitop3:0x6c
	v_lshl_add_u32 v1, s4, 13, v185
	s_add_i32 s78, s75, 0x8000
	s_mov_b32 s8, m0
	s_mov_b32 m0, s78
	s_nop 0
	global_load_lds_dwordx4 v1, s[22:23]
	s_mov_b32 m0, s8
	v_lshlrev_b32_e32 v0, 4, v0
	s_add_i32 s79, s75, 0xa000
	s_mov_b32 s8, m0
	s_mov_b32 m0, s79
	s_nop 0
	global_load_lds_dwordx4 v1, s[24:25]
	s_mov_b32 m0, s8
	v_add_u32_e32 v171, v9, v0
	s_waitcnt vmcnt(0) lgkmcnt(0)
	s_barrier
	ds_read_b128 v[0:3], v171
	ds_read_b128 v[4:7], v171 offset:4096
	s_waitcnt lgkmcnt(1)
	v_mfma_f32_32x32x16_bf16 v[16:31], v[0:3], v[144:147], 0
	v_or_b32_e32 v0, 2, v33
	v_bitop3_b32 v0, v8, v0, 7 bitop3:0x6c
	v_lshlrev_b32_e32 v0, 4, v0
	v_add_u32_e32 v174, v9, v0
	ds_read_b128 v[0:3], v174
	ds_read_b128 v[38:41], v174 offset:4096
	s_add_i32 s70, s70, 2
	s_cmp_lt_i32 s70, 3
	s_waitcnt lgkmcnt(1)
	v_mfma_f32_32x32x16_bf16 v[16:31], v[0:3], v[140:143], v[16:31]
	v_or_b32_e32 v0, 4, v33
	v_bitop3_b32 v0, v8, v0, 7 bitop3:0x6c
	v_lshlrev_b32_e32 v0, 4, v0
	v_add_u32_e32 v172, v9, v0
	ds_read_b128 v[0:3], v172
	ds_read_b128 v[42:45], v172 offset:4096
	s_waitcnt lgkmcnt(1)
	v_mfma_f32_32x32x16_bf16 v[16:31], v[0:3], v[136:139], v[16:31]
	v_or_b32_e32 v0, 6, v33
	v_bitop3_b32 v0, v8, v0, 7 bitop3:0x6c
	v_lshlrev_b32_e32 v0, 4, v0
	v_add_u32_e32 v173, v9, v0
	ds_read_b128 v[0:3], v173
	ds_read_b128 v[46:49], v173 offset:4096
	s_waitcnt lgkmcnt(0)
	s_barrier
	s_waitcnt lgkmcnt(1)
	v_mfma_f32_32x32x16_bf16 v[16:31], v[0:3], v[132:135], v[16:31]
	v_mfma_f32_32x32x16_bf16 v[0:15], v[4:7], v[144:147], 0
	v_mfma_f32_32x32x16_bf16 v[0:15], v[38:41], v[140:143], v[0:15]
	v_mfma_f32_32x32x16_bf16 v[0:15], v[42:45], v[136:139], v[0:15]
	s_waitcnt lgkmcnt(0)
	v_mfma_f32_32x32x16_bf16 v[0:15], v[46:49], v[132:135], v[0:15]
	s_cbranch_scc1 .LBB0_255
	s_lshl_b32 s8, s72, 13
	s_add_i32 s9, s8, 0x4000
	s_cmp_lt_i32 s72, s71
	s_cselect_b32 s8, s8, s9
	v_add_u32_e32 v38, s8, v185
	s_mov_b32 s8, m0
	s_mov_b32 m0, s75
	s_nop 0
	global_load_lds_dwordx4 v38, s[22:23]
	s_mov_b32 m0, s8
	s_nop 0
	s_mov_b32 s8, m0
	s_mov_b32 m0, s77
	s_nop 0
	global_load_lds_dwordx4 v38, s[24:25]
	s_mov_b32 m0, s8

.LBB0_296:
	s_andn2_b64 vcc, exec, s[4:5]
	s_cbranch_vccnz .LBB0_244
	v_mov_b32_e32 v32, v254
	s_and_b32 s9, s68, 63
	v_readfirstlane_b32 s36, v32
	s_ashr_i32 s8, s36, 6
	s_and_b32 s69, s8, 3
	s_cmp_lg_u32 s37, 1
	s_cbranch_scc1 .Lsp_skip2
	s_setprio 1
.Lsp_skip2:
	s_ashr_i32 s74, s68, 7
	s_lshl_b32 s5, s9, 7
	s_lshl_b32 s4, s69, 5
	s_ashr_i32 s37, s36, 8
	s_sub_i32 s26, 3, s74
	s_bfe_u32 s27, s68, 0x10006
	s_or_b32 s4, s4, s5
	s_cmp_eq_u32 s74, 1
	v_mov_b32_e32 v0, s62
	v_mov_b32_e32 v1, s61
	s_cselect_b64 vcc, -1, 0
	v_cndmask_b32_e32 v0, v0, v1, vcc
	v_cvt_i32_f32_e32 v0, v0
	v_and_or_b32 v159, v32, 31, s4
	v_bfe_u32 v34, v32, 4, 2
	v_bfe_u32 v33, v32, 5, 1
	v_readfirstlane_b32 s4, v0
	s_sub_i32 s6, s5, s4
	s_sub_i32 s7, s6, 63
	s_ashr_i32 s6, s6, 6
	s_cmp_gt_i32 s7, 0
	s_cselect_b32 s70, s6, 0
	s_add_i32 s4, s4, s5
	s_addk_i32 s4, 0x7f
	s_ashr_i32 s6, s4, 6
	s_lshl_b32 s68, s9, 1
	s_or_b32 s4, s68, 1
	s_min_i32 s6, s6, 0x7f
	s_sub_i32 s7, s68, s70
	s_sub_i32 s6, s6, s4
	s_add_i32 s78, s7, s6
	s_lshl_b32 s6, s27, 3
	s_lshl_b32 s7, s26, 1
	s_add_i32 s20, s6, s7
	s_lshl_b64 s[6:7], s[20:21], 20
	s_add_u32 s22, s45, s6
	s_addc_u32 s23, s46, s7
	s_add_u32 s24, s22, 0x100000
	v_bfe_u32 v0, v32, 3, 3
	s_addc_u32 s25, s23, 0
	s_lshl_b32 s6, s27, 2
	s_add_i32 s28, s37, s20
	v_lshl_or_b32 v2, s8, 3, v0
	s_add_i32 s6, s6, s26
	s_mov_b32 s7, s21
	s_ashr_i32 s29, s28, 31
	v_lshrrev_b32_e32 v0, 1, v2
	s_lshl_b64 s[6:7], s[6:7], 21
	s_lshl_b32 s8, s8, 10
	s_lshl_b64 s[28:29], s[28:29], 20
	v_xor_b32_e32 v0, v0, v32
	s_add_u32 s28, s38, s28
	v_lshlrev_b32_e32 v3, 4, v0
	v_and_b32_e32 v36, 15, v32
	v_lshlrev_b32_e32 v0, 2, v34
	s_addc_u32 s29, s44, s29
	v_lshlrev_b32_e32 v130, 7, v159
	v_bitop3_b32 v5, v0, v36, s69 bitop3:0x36
	v_lshl_add_u64 v[0:1], s[28:29], 0, v[130:131]
	v_lshlrev_b32_e32 v156, 4, v33
	v_mov_b32_e32 v157, v131
	v_lshl_add_u64 v[0:1], v[0:1], 0, v[156:157]
	s_waitcnt vmcnt(0)
	global_load_dwordx4 v[144:147], v[0:1], off
	global_load_dwordx4 v[140:143], v[0:1], off offset:32
	global_load_dwordx4 v[136:139], v[0:1], off offset:64
	global_load_dwordx4 v[132:135], v[0:1], off offset:96
	v_lshlrev_b32_e32 v1, 1, v32
	v_lshrrev_b32_e32 v37, 1, v32
	v_and_b32_e32 v0, 19, v32
	v_and_b32_e32 v1, 8, v1
	v_and_b32_e32 v6, 4, v37
	v_or3_b32 v35, v6, v0, v1
	v_lshlrev_b32_e32 v0, 7, v2
	s_add_u32 s6, s47, s6
	v_and_or_b32 v185, v3, s64, v0
	v_lshl_or_b32 v4, v34, 8, s8
	s_addc_u32 s7, s48, s7
	v_lshl_add_u32 v1, s9, 14, v185
	s_add_i32 s73, s8, 0
	s_mov_b32 s8, m0
	s_mov_b32 m0, s73
	s_nop 0
	global_load_lds_dwordx4 v1, s[22:23]
	s_mov_b32 m0, s8
	s_add_i32 s75, s73, 0x2000
	s_mov_b32 s8, m0
	s_mov_b32 m0, s75
	s_nop 0
	global_load_lds_dwordx4 v1, s[24:25]
	s_mov_b32 m0, s8
	v_lshl_or_b32 v170, v5, 4, v4
	s_lshl_b32 s20, s37, 13
	s_lshl_b32 s8, s9, 15
	v_lshrrev_b32_e32 v8, 1, v35
	v_add_u32_e32 v169, 0x2000, v170
	v_lshl_or_b32 v0, v35, 7, s20
	v_add_u32_e32 v1, s8, v170
	s_add_i32 s71, s73, 0x4000
	s_mov_b32 s9, m0
	s_mov_b32 m0, s71
	s_nop 0
	global_load_lds_dwordx4 v1, s[6:7]
	s_mov_b32 m0, s9
	v_add_u32_e32 v1, s8, v169
	s_add_i32 s72, s73, 0x6000
	s_mov_b32 s8, m0
	s_mov_b32 m0, s72
	s_nop 0
	global_load_lds_dwordx4 v1, s[6:7]
	s_mov_b32 m0, s8
	v_add_u32_e32 v9, 0, v0
	v_bitop3_b32 v0, v8, v33, 7 bitop3:0x6c
	v_lshl_add_u32 v1, s4, 13, v185
	s_add_i32 s76, s73, 0x8000
	s_mov_b32 s8, m0
	s_mov_b32 m0, s76
	s_nop 0
	global_load_lds_dwordx4 v1, s[22:23]
	s_mov_b32 m0, s8
	v_lshlrev_b32_e32 v0, 4, v0
	s_add_i32 s77, s73, 0xa000
	s_mov_b32 s8, m0
	s_mov_b32 m0, s77
	s_nop 0
	global_load_lds_dwordx4 v1, s[24:25]
	s_mov_b32 m0, s8
	v_add_u32_e32 v171, v9, v0
	s_waitcnt vmcnt(0) lgkmcnt(0)
	s_barrier
	ds_read_b128 v[0:3], v171
	ds_read_b128 v[4:7], v171 offset:4096
	s_waitcnt lgkmcnt(1)
	v_mfma_f32_32x32x16_bf16 v[16:31], v[0:3], v[144:147], 0
	v_or_b32_e32 v0, 2, v33
	v_bitop3_b32 v0, v8, v0, 7 bitop3:0x6c
	v_lshlrev_b32_e32 v0, 4, v0
	v_add_u32_e32 v174, v9, v0
	ds_read_b128 v[0:3], v174
	ds_read_b128 v[38:41], v174 offset:4096
	s_add_i32 s20, s78, 2
	s_cmp_lt_i32 s20, 3
	s_waitcnt lgkmcnt(1)
	v_mfma_f32_32x32x16_bf16 v[16:31], v[0:3], v[140:143], v[16:31]
	v_or_b32_e32 v0, 4, v33
	v_bitop3_b32 v0, v8, v0, 7 bitop3:0x6c
	v_lshlrev_b32_e32 v0, 4, v0
	v_add_u32_e32 v172, v9, v0
	ds_read_b128 v[0:3], v172
	ds_read_b128 v[42:45], v172 offset:4096
	s_waitcnt lgkmcnt(1)
	v_mfma_f32_32x32x16_bf16 v[16:31], v[0:3], v[136:139], v[16:31]
	v_or_b32_e32 v0, 6, v33
	v_bitop3_b32 v0, v8, v0, 7 bitop3:0x6c
	v_lshlrev_b32_e32 v0, 4, v0
	v_add_u32_e32 v173, v9, v0
	ds_read_b128 v[0:3], v173
	ds_read_b128 v[46:49], v173 offset:4096
	s_waitcnt lgkmcnt(0)
	s_barrier
	s_waitcnt lgkmcnt(1)
	v_mfma_f32_32x32x16_bf16 v[16:31], v[0:3], v[132:135], v[16:31]
	v_mfma_f32_32x32x16_bf16 v[0:15], v[4:7], v[144:147], 0
	v_mfma_f32_32x32x16_bf16 v[0:15], v[38:41], v[140:143], v[0:15]
	v_mfma_f32_32x32x16_bf16 v[0:15], v[42:45], v[136:139], v[0:15]
	s_waitcnt lgkmcnt(0)
	v_mfma_f32_32x32x16_bf16 v[0:15], v[46:49], v[132:135], v[0:15]
	s_cbranch_scc1 .LBB0_299
	s_lshl_b32 s8, s70, 13
	s_add_i32 s9, s8, 0x4000
	s_cmp_lt_i32 s70, s68
	s_cselect_b32 s8, s8, s9
	v_add_u32_e32 v38, s8, v185
	s_mov_b32 s8, m0
	s_mov_b32 m0, s73
	s_nop 0
	global_load_lds_dwordx4 v38, s[22:23]
	s_mov_b32 m0, s8
	s_nop 0
	s_mov_b32 s8, m0
	s_mov_b32 m0, s75
	s_nop 0
	global_load_lds_dwordx4 v38, s[24:25]
	s_mov_b32 m0, s8
